# v6 plus attention PV reads batched (counted lgkmcnt) and sample K/V prefetch waits relaxed
# baseline (speedup 1.0000x reference)
.LBB0_1367:
	s_lshl_b32 s86, s0, 3
	s_addk_i32 s86, 0x1fc0
	s_and_b64 vcc, exec, s[20:21]
	s_cbranch_vccz .LBB0_1375
	v_lshl_add_u64 v[2:3], s[16:17], 0, v[168:169]
	v_lshlrev_b64 v[2:3], 8, v[2:3]
	v_lshl_add_u64 v[2:3], v[170:171], 0, v[2:3]
	global_load_dwordx4 v[6:9], v[2:3], off offset:16
	s_nop 0
	global_load_dwordx4 v[2:5], v[2:3], off
	s_and_saveexec_b64 s[20:21], s[38:39]
	s_xor_b64 s[20:21], exec, s[20:21]
	s_cbranch_execz .LBB0_1372
	v_mov_b32_e32 v50, v51
	v_mov_b32_e32 v52, v51
	v_mov_b32_e32 v53, v51
	v_mov_b64_e32 v[14:15], v[50:51]
	v_mov_b64_e32 v[16:17], v[52:53]
	s_and_saveexec_b64 s[34:35], s[56:57]
	s_cbranch_execz .LBB0_1371
	v_add_u32_e32 v10, s86, v158
	v_ashrrev_i32_e32 v11, 31, v10
	v_lshlrev_b64 v[10:11], 9, v[10:11]
	v_lshl_add_u64 v[10:11], s[12:13], 0, v[10:11]
	v_lshlrev_b32_e32 v50, 1, v166
	v_lshl_add_u64 v[10:11], v[10:11], 0, v[50:51]
	global_load_dwordx4 v[14:17], v[10:11], off

.LBB0_1372:
	s_or_saveexec_b64 s[20:21], s[20:21]
	v_mov_b32_e32 v50, v51
	v_mov_b32_e32 v52, v51
	v_mov_b32_e32 v53, v51
	v_mov_b64_e32 v[10:11], v[50:51]
	v_mov_b64_e32 v[12:13], v[52:53]
	s_xor_b64 exec, exec, s[20:21]
	s_cbranch_execz .LBB0_1374
	s_lshl_b64 s[34:35], s[10:11], 8
	v_lshl_add_u64 v[10:11], v[172:173], 0, s[34:35]
	s_lshl_b64 s[34:35], s[0:1], 17
	v_lshl_add_u64 v[14:15], v[10:11], 0, s[34:35]
	global_load_dwordx4 v[10:13], v[14:15], off offset:16
	s_nop 0
	global_load_dwordx4 v[14:17], v[14:15], off

.LBB0_1383:
	s_and_b64 vcc, exec, s[34:35]
	s_cbranch_vccz .LBB0_1397
	s_and_saveexec_b64 s[34:35], s[44:45]
	s_xor_b64 s[34:35], exec, s[34:35]
	s_cbranch_execz .LBB0_1388
	v_mov_b32_e32 v21, 0
	v_mov_b32_e32 v20, 0
	v_mov_b32_e32 v19, 0
	v_mov_b32_e32 v18, 0
	s_and_saveexec_b64 s[80:81], s[58:59]
	s_cbranch_execz .LBB0_1387
	v_add_u32_e32 v18, s86, v198
	v_ashrrev_i32_e32 v19, 31, v18
	v_lshlrev_b64 v[18:19], 9, v[18:19]
	v_lshl_add_u64 v[18:19], v[110:111], 0, v[18:19]
	global_load_dwordx4 v[18:21], v[18:19], off

.LBB0_1388:
	s_or_saveexec_b64 s[34:35], s[34:35]
	v_mov_b32_e32 v22, 0
	v_mov_b32_e32 v23, 0
	v_mov_b32_e32 v24, 0
	v_mov_b32_e32 v25, 0
	s_xor_b64 exec, exec, s[34:35]
	s_cbranch_execz .LBB0_1390
	v_lshl_add_u64 v[18:19], s[16:17], 0, v[176:177]
	v_lshlrev_b64 v[18:19], 8, v[18:19]
	v_lshl_add_u64 v[22:23], v[170:171], 0, v[18:19]
	global_load_dwordx4 v[18:21], v[22:23], off
	s_nop 0
	global_load_dwordx4 v[22:25], v[22:23], off offset:16

.LBB0_1394:
	s_or_saveexec_b64 s[16:17], s[16:17]
	v_mov_b32_e32 v50, v51
	v_mov_b32_e32 v52, v51
	v_mov_b32_e32 v53, v51
	v_mov_b64_e32 v[30:31], v[50:51]
	v_mov_b64_e32 v[32:33], v[52:53]
	s_xor_b64 exec, exec, s[16:17]
	s_cbranch_execz .LBB0_1396
	s_lshl_b64 s[34:35], s[10:11], 8
	v_lshl_add_u64 v[26:27], v[178:179], 0, s[34:35]
	s_lshl_b64 s[34:35], s[0:1], 17
	v_lshl_add_u64 v[26:27], v[26:27], 0, s[34:35]
	global_load_dwordx4 v[30:33], v[26:27], off offset:16
	s_nop 0
	global_load_dwordx4 v[26:29], v[26:27], off

.LBB0_1405:
	s_and_b64 vcc, exec, s[20:21]
	s_cbranch_vccz .LBB0_1415
	v_mov_b32_e32 v34, 0
	v_mov_b32_e32 v35, 0
	v_mov_b32_e32 v36, 0
	v_mov_b32_e32 v37, 0
	s_and_saveexec_b64 s[20:21], s[62:63]
	s_cbranch_execz .LBB0_1408
	v_add_u32_e32 v34, s86, v202
	v_ashrrev_i32_e32 v35, 31, v34
	v_lshlrev_b64 v[34:35], 9, v[34:35]
	v_lshl_add_u64 v[34:35], v[110:111], 0, v[34:35]
	global_load_dwordx4 v[34:37], v[34:35], off
